# v52_mobapro1
# speedup vs baseline: 1.0126x; 1.0049x over previous
; DEVI void moba_item(const Params& p, int l, int item) {
;   const int tid_ = get_tid();
;   const int bh = item & 15, r = item >> 4;
;   const int qt = (r < 16) ? 31 - r : r - 16;
;   const int b = bh >> 3, h = bh & 7, qblk = qt >> 1;
;   const long t0 = (long)b * S_ + qt * 128;
;   const int tid = tid_, w = tid >> 6, lane = tid & 63, fr = lane & 15, fq = lane >> 4;
;   const u16* proj = p.proj;
;   u16* Kb0 = (u16*)smem;                u16* Vb0 = (u16*)(smem + 34816);
;   u16* Kb1 = (u16*)(smem + 71680);      u16* Vb1 = (u16*)(smem + 71680 + 34816);
;   u16* Qs = Kb1;
;   float* km = (float*)(smem + 71680 + 34816);
;   float* gate = (float*)(smem + 71680 + 34816 + 8192);
;   unsigned* selm = (unsigned*)(smem + 71680 + 34816 + 8192 + 8704);
;   const int kkey = tid >> 4, kdg = tid & 15;
;   bf16x8 pk_[4], pv_[4];
;   {
;     const long tb = (long)b * S_ + qblk * 256;
; #pragma unroll
;     for (int i = 0; i < 4; ++i) {
;       pk_[i] = *(const bf16x8*)(proj + (tb + kkey + 32 * i) * NP + C_CK + h * 128 + kdg * 8);
;       pv_[i] = *(const bf16x8*)(proj + (tb + kkey + 32 * i) * NP + C_CV + h * 128 + kdg * 8);
;     }
;   }
; #pragma unroll
;   for (int i = 0; i < 4; ++i) {
;     int ch = tid + i * 512;
;     int row = ch >> 4, dg = ch & 15;
;     *(bf16x8*)(Qs + row * 136 + dg * 8) = *(const bf16x8*)(proj + (t0 + row) * NP + C_CQ + h * 128 + dg * 8);
;   }
;   for (int i = tid; i < qblk * 128; i += 512) km[i] = p.kmean[(long)(bh * 16) * 128 + i];
;   if (tid == 0) selm[128] = 0u;
;   __syncthreads();
.LBB0_494:
	s_ashr_i32 s2, s26, 4
	s_sub_i32 s3, 31, s2
	s_add_i32 s6, s2, -16
	s_cmp_lt_i32 s2, 16
	s_cselect_b32 s20, s3, s6
	s_lshr_b32 s28, s20, 1
	s_lshl_b32 s2, s26, 9
	s_waitcnt vmcnt(0)
	v_mov_b32_e32 v48, v234
	s_and_b32 s29, s2, 0x1000
	s_lshl_b32 s2, s28, 8
	s_add_i32 s2, s2, s29
	v_lshrrev_b32_e32 v154, 4, v48
	v_or_b32_e32 v24, s2, v154
	s_lshl_b32 s2, s26, 7
	s_and_b32 s6, s2, 0x380
	v_mov_b64_e32 v[36:37], s[92:93]
	v_and_b32_e32 v50, 15, v48
	v_mad_u64_u32 v[0:1], s[2:3], v24, s97, v[36:37]
	s_lshl_b32 s98, s6, 1
	v_lshlrev_b32_e32 v210, 4, v50
	v_lshl_add_u64 v[0:1], v[0:1], 0, s[98:99]
	v_or_b32_e32 v8, 32, v24
	v_lshl_add_u64 v[0:1], v[0:1], 0, v[210:211]
	v_mad_u64_u32 v[8:9], s[2:3], v8, s97, v[36:37]
	v_add_co_u32_e32 v4, vcc, s68, v0
	v_lshl_add_u64 v[8:9], v[8:9], 0, s[98:99]
	v_or_b32_e32 v16, 64, v24
	v_addc_co_u32_e32 v5, vcc, 0, v1, vcc
	v_lshl_add_u64 v[8:9], v[8:9], 0, v[210:211]
	v_mad_u64_u32 v[16:17], s[2:3], v16, s97, v[36:37]
	s_lshl_b32 s27, s20, 7
	v_add_co_u32_e32 v12, vcc, s68, v8
	v_lshl_add_u64 v[16:17], v[16:17], 0, s[98:99]
	v_or_b32_e32 v24, 0x60, v24
	s_add_i32 s27, s27, s29
	v_addc_co_u32_e32 v13, vcc, 0, v9, vcc
	v_lshl_add_u64 v[16:17], v[16:17], 0, v[210:211]
	v_mad_u64_u32 v[24:25], s[2:3], v24, s97, v[36:37]
	v_add_co_u32_e32 v20, vcc, s68, v16
	v_lshl_add_u64 v[24:25], v[24:25], 0, s[98:99]
	v_lshlrev_b32_e32 v32, 4, v48
	v_or_b32_e32 v38, s27, v154
	v_addc_co_u32_e32 v21, vcc, 0, v17, vcc
	v_lshl_add_u64 v[24:25], v[24:25], 0, v[210:211]
	v_and_b32_e32 v210, 0xf0, v32
	v_mad_u64_u32 v[32:33], s[2:3], v38, s97, v[36:37]
	v_add_co_u32_e32 v28, vcc, s68, v24
	v_lshl_add_u64 v[32:33], v[32:33], 0, s[98:99]
	s_nop 0
	v_addc_co_u32_e32 v29, vcc, 0, v25, vcc
	v_lshl_add_u64 v[32:33], v[32:33], 0, v[210:211]
	v_add_co_u32_e32 v32, vcc, s57, v32
	s_nop 1
	v_addc_co_u32_e32 v33, vcc, 0, v33, vcc
	v_mul_u32_u24_e32 v155, 0x110, v154
	global_load_dwordx4 v[180:183], v[32:33], off offset:2560
	v_add3_u32 v196, s70, v210, v155
	s_lshl_b32 s10, s28, 7
	v_or_b32_e32 v32, 32, v38
	v_mad_u64_u32 v[32:33], s[2:3], v32, s97, v[36:37]
	v_lshl_add_u64 v[32:33], v[32:33], 0, s[98:99]
	v_lshl_add_u64 v[32:33], v[32:33], 0, v[210:211]
	v_add_co_u32_e32 v32, vcc, s57, v32
	s_nop 1
	v_addc_co_u32_e32 v33, vcc, 0, v33, vcc
	global_load_dwordx4 v[184:187], v[32:33], off offset:2560
	v_or_b32_e32 v32, 64, v38
	v_mad_u64_u32 v[32:33], s[2:3], v32, s97, v[36:37]
	v_lshl_add_u64 v[32:33], v[32:33], 0, s[98:99]
	v_lshl_add_u64 v[32:33], v[32:33], 0, v[210:211]
	v_add_co_u32_e32 v32, vcc, s57, v32
	s_nop 1
	v_addc_co_u32_e32 v33, vcc, 0, v33, vcc
	global_load_dwordx4 v[188:191], v[32:33], off offset:2560
	v_or_b32_e32 v32, 0x60, v38
	v_mad_u64_u32 v[32:33], s[2:3], v32, s97, v[36:37]
	v_lshl_add_u64 v[32:33], v[32:33], 0, s[98:99]
	v_lshl_add_u64 v[32:33], v[32:33], 0, v[210:211]
	v_add_co_u32_e32 v32, vcc, 0x2000, v32
	s_nop 1
	v_addc_co_u32_e32 v33, vcc, 0, v33, vcc
	global_load_dwordx4 v[192:195], v[32:33], off offset:2560
	s_and_b32 s11, s26, 15
	s_lshl_b32 s21, s11, 11
	v_add_u32_e32 v210, s21, v48
	v_lshl_add_u32 v36, v48, 2, s72
	v_lshl_add_u64 v[40:41], v[210:211], 2, s[44:45]
	v_add_u32_e32 v37, 0x200, v48
	v_add_u32_e32 v38, 0x400, v48
	v_add_co_u32_e32 v42, vcc, 0x1000, v40
	v_add_u32_e32 v39, 0x600, v48
	s_nop 1
	v_addc_co_u32_e32 v43, vcc, 0, v41, vcc
	v_cmp_gt_u32_e32 vcc, s10, v48
	s_and_saveexec_b64 s[6:7], vcc
	global_load_dword v197, v[40:41], off
	s_mov_b64 exec, s[6:7]
	v_cmp_gt_u32_e32 vcc, s10, v37
	s_and_saveexec_b64 s[6:7], vcc
	global_load_dword v198, v[40:41], off offset:2048
	s_mov_b64 exec, s[6:7]
	v_cmp_gt_u32_e32 vcc, s10, v38
	s_and_saveexec_b64 s[6:7], vcc
	global_load_dword v199, v[42:43], off
	s_mov_b64 exec, s[6:7]
	v_cmp_gt_u32_e32 vcc, s10, v39
	s_and_saveexec_b64 s[6:7], vcc
	global_load_dword v200, v[42:43], off offset:2048
	s_mov_b64 exec, s[6:7]
	global_load_dwordx4 v[0:3], v[4:5], off offset:512
	s_nop 0
	global_load_dwordx4 v[4:7], v[4:5], off offset:2560
	s_nop 0
	global_load_dwordx4 v[8:11], v[12:13], off offset:512
	s_nop 0
	global_load_dwordx4 v[12:15], v[12:13], off offset:2560
	s_nop 0
	global_load_dwordx4 v[16:19], v[20:21], off offset:512
	s_nop 0
	global_load_dwordx4 v[20:23], v[20:21], off offset:2560
	s_nop 0
	global_load_dwordx4 v[24:27], v[28:29], off offset:512
	s_nop 0
	global_load_dwordx4 v[28:31], v[28:29], off offset:2560
	s_nop 0
	s_waitcnt vmcnt(8)
	ds_write_b128 v196, v[180:183]
	ds_write_b128 v196, v[184:187] offset:8704
	ds_write_b128 v196, v[188:191] offset:17408
	ds_write_b128 v196, v[192:195] offset:26112
	v_cmp_gt_u32_e32 vcc, s10, v48
	s_and_saveexec_b64 s[6:7], vcc
	ds_write_b32 v36, v197
	s_mov_b64 exec, s[6:7]
	v_cmp_gt_u32_e32 vcc, s10, v37
	s_and_saveexec_b64 s[6:7], vcc
	ds_write_b32 v36, v198 offset:2048
	s_mov_b64 exec, s[6:7]
	v_cmp_gt_u32_e32 vcc, s10, v38
	s_and_saveexec_b64 s[6:7], vcc
	ds_write_b32 v36, v199 offset:4096
	s_mov_b64 exec, s[6:7]
	v_cmp_gt_u32_e32 vcc, s10, v39
	s_and_saveexec_b64 s[6:7], vcc
	ds_write_b32 v36, v200 offset:6144
	s_mov_b64 exec, s[6:7]
	v_cmp_eq_u32_e32 vcc, 0, v48
	s_and_saveexec_b64 s[2:3], vcc
	v_mov_b32_e32 v32, s73
	ds_write_b32 v32, v211
	s_or_b64 exec, exec, s[2:3]
	v_and_b32_e32 v40, 0x7f, v48
	v_mad_u32_u24 v32, v40, s71, 0
	v_add_u32_e32 v32, 0x11800, v32
	s_waitcnt lgkmcnt(0)
	s_barrier
; DEVI float bfs(short h) { return __uint_as_float(((unsigned)(u16)h) << 16); }
; DEVI void moba_item(const Params& p, int l, int item) {
;     ...
;   {
;     const int q = tid & 127, part = tid >> 7;
;     float dots[4] = {0.f, 0.f, 0.f, 0.f};
; #pragma unroll
;     for (int c = 0; c < 16; ++c) {
;       const bf16x8 qv = *(const bf16x8*)(Qs + q * 136 + c * 8);
;       float qf[8];
; #pragma unroll
;       for (int e = 0; e < 8; ++e) qf[e] = bfs(qv[e]);
; #pragma unroll
;       for (int k = 0; k < 4; ++k) {
;         const int blk = part + 4 * k;
;         if (blk < qblk) {
; #pragma unroll
;           for (int e = 0; e < 8; ++e) dots[k] += qf[e] * km[blk * 128 + c * 8 + e];
;         }
;       }
;     }
	v_lshrrev_b32_e32 v35, 7, v48
	v_mov_b32_e32 v36, 0
	v_readfirstlane_b32 s2, v35
	s_sub_i32 s3, s28, s2
	s_add_i32 s3, s3, 3
	s_ashr_i32 s3, s3, 2
	s_cmp_lt_i32 s3, 1
	s_cbranch_scc1 .Lmy_gd_done
	v_lshl_add_u32 v33, v35, 9, s72
	v_mov_b32_e32 v37, 0
	v_mov_b32_e32 v38, 0
	v_mov_b32_e32 v39, 0
	ds_read_b128 v[56:59], v32
	ds_read_b128 v[60:63], v33
	ds_read_b128 v[64:67], v33 offset:16
	ds_read_b128 v[68:71], v33 offset:2048
	ds_read_b128 v[72:75], v33 offset:2064
	ds_read_b128 v[76:79], v33 offset:4096
	ds_read_b128 v[80:83], v33 offset:4112
	ds_read_b128 v[84:87], v33 offset:6144
	ds_read_b128 v[88:91], v33 offset:6160
	ds_read_b128 v[92:95], v32 offset:16
	ds_read_b128 v[96:99], v33 offset:32
	ds_read_b128 v[100:103], v33 offset:48
	ds_read_b128 v[104:107], v33 offset:2080
	ds_read_b128 v[108:111], v33 offset:2096
	ds_read_b128 v[112:115], v33 offset:4128
	ds_read_b128 v[116:119], v33 offset:4144
	ds_read_b128 v[120:123], v33 offset:6176
	ds_read_b128 v[124:127], v33 offset:6192
	s_waitcnt lgkmcnt(9)
	v_lshlrev_b32_e32 v128, 16, v56
	v_and_b32_e32 v129, 0xffff0000, v56
	v_lshlrev_b32_e32 v130, 16, v57
	v_and_b32_e32 v131, 0xffff0000, v57
	v_lshlrev_b32_e32 v132, 16, v58
	v_and_b32_e32 v133, 0xffff0000, v58
	v_lshlrev_b32_e32 v134, 16, v59
	v_and_b32_e32 v135, 0xffff0000, v59
	v_pk_mul_f32 v[136:137], v[60:61], v[128:129]
	v_pk_mul_f32 v[138:139], v[62:63], v[130:131]
	v_pk_mul_f32 v[140:141], v[64:65], v[132:133]
	v_pk_mul_f32 v[142:143], v[66:67], v[134:135]
	v_add_f32_e32 v36, v36, v136
	v_add_f32_e32 v36, v36, v137
	v_add_f32_e32 v36, v36, v138
	v_add_f32_e32 v36, v36, v139
	v_add_f32_e32 v36, v36, v140
	v_add_f32_e32 v36, v36, v141
	v_add_f32_e32 v36, v36, v142
	v_add_f32_e32 v36, v36, v143
	s_cmp_lt_i32 s3, 2
	s_cbranch_scc1 .Lmy_gd_c0
	v_pk_mul_f32 v[136:137], v[68:69], v[128:129]
	v_pk_mul_f32 v[138:139], v[70:71], v[130:131]
	v_pk_mul_f32 v[140:141], v[72:73], v[132:133]
	v_pk_mul_f32 v[142:143], v[74:75], v[134:135]
	v_add_f32_e32 v37, v37, v136
	v_add_f32_e32 v37, v37, v137
	v_add_f32_e32 v37, v37, v138
	v_add_f32_e32 v37, v37, v139
	v_add_f32_e32 v37, v37, v140
	v_add_f32_e32 v37, v37, v141
	v_add_f32_e32 v37, v37, v142
	v_add_f32_e32 v37, v37, v143
	s_cmp_lt_i32 s3, 3
	s_cbranch_scc1 .Lmy_gd_c0
	v_pk_mul_f32 v[136:137], v[76:77], v[128:129]
	v_pk_mul_f32 v[138:139], v[78:79], v[130:131]
	v_pk_mul_f32 v[140:141], v[80:81], v[132:133]
	v_pk_mul_f32 v[142:143], v[82:83], v[134:135]
	v_add_f32_e32 v38, v38, v136
	v_add_f32_e32 v38, v38, v137
	v_add_f32_e32 v38, v38, v138
	v_add_f32_e32 v38, v38, v139
	v_add_f32_e32 v38, v38, v140
	v_add_f32_e32 v38, v38, v141
	v_add_f32_e32 v38, v38, v142
	v_add_f32_e32 v38, v38, v143
	s_cmp_lt_i32 s3, 4
	s_cbranch_scc1 .Lmy_gd_c0
	v_pk_mul_f32 v[136:137], v[84:85], v[128:129]
	v_pk_mul_f32 v[138:139], v[86:87], v[130:131]
	v_pk_mul_f32 v[140:141], v[88:89], v[132:133]
	v_pk_mul_f32 v[142:143], v[90:91], v[134:135]
	v_add_f32_e32 v39, v39, v136
	v_add_f32_e32 v39, v39, v137
	v_add_f32_e32 v39, v39, v138
	v_add_f32_e32 v39, v39, v139
	v_add_f32_e32 v39, v39, v140
	v_add_f32_e32 v39, v39, v141
	v_add_f32_e32 v39, v39, v142
	v_add_f32_e32 v39, v39, v143

; DEVI void moba_item(const Params& p, int l, int item) {
;     ...
;   bf16x8 qb[4];
; #pragma unroll
;   for (int ks = 0; ks < 4; ++ks) qb[ks] = *(const bf16x8*)(Qs + (w * 16 + fr) * 136 + ks * 32 + fq * 8);
; #pragma unroll
;   for (int i = 0; i < 4; ++i) {
;     *(bf16x8*)(Kb0 + (kkey + 32 * i) * 136 + kdg * 8) = pk_[i];
;     *(bf16x8*)(Vb0 + (kkey + 32 * i) * 144 + kdg * 8) = pv_[i];
;   }
;   __syncthreads();
;   unsigned pend = selm[128];
;   const unsigned mysel = selm[w * 16 + fr];
;   __syncthreads();
;   float m = -INFINITY, lsum = 0.f;
;   f32x4 oacc[8];
; #pragma unroll
;   for (int ct = 0; ct < 8; ++ct) oacc[ct] = f32x4{0.f, 0.f, 0.f, 0.f};
;   const int qinb = (qt & 1) * 128 + w * 16 + fr;
;   int cblk = qblk, chalf = 0;
;   int nblk, nhalf;
;     ...
;   MOBA_NEXT(cblk, chalf, nblk, nhalf);
;   if (nblk >= 0) MOBA_LOAD(nblk, nhalf);
.LBB0_653:
	s_or_b64 exec, exec, s[2:3]
	s_waitcnt vmcnt(0)
	v_lshrrev_b32_e32 v32, 2, v48
	v_and_b32_e32 v51, 0x70, v32
	v_lshlrev_b32_e32 v52, 3, v50
	v_and_b32_e32 v49, 3, v154
	v_or_b32_e32 v156, v51, v50
	v_mul_u32_u24_e32 v32, 0x110, v156
	v_lshlrev_b32_e32 v33, 4, v49
	v_lshl_add_u32 v53, v52, 1, 0
	v_add3_u32 v44, s70, v32, v33
	v_add_u32_e32 v54, v53, v155
	v_mad_u32_u24 v53, v154, s75, v53
	ds_read_b128 v[32:35], v44
	ds_read_b128 v[36:39], v44 offset:64
	ds_read_b128 v[40:43], v44 offset:128
	ds_read_b128 v[44:47], v44 offset:192
	ds_write_b128 v54, v[0:3]
	ds_write_b128 v53, v[4:7] offset:34816
	ds_write_b128 v54, v[8:11] offset:8704
	ds_write_b128 v53, v[12:15] offset:44032
	ds_write_b128 v54, v[16:19] offset:17408
	ds_write_b128 v53, v[20:23] offset:53248
	ds_write_b128 v54, v[24:27] offset:26112
	ds_write_b128 v53, v[28:31] offset:62464
	v_mov_b32_e32 v53, s73
	s_waitcnt lgkmcnt(0)
	s_barrier
	ds_read_b32 v53, v53
	s_and_b32 s8, s20, 1
	v_lshl_add_u32 v54, v156, 2, 0
	s_lshl_b32 s3, s8, 7
	v_add_u32_e32 v54, 0x1e200, v54
	s_waitcnt lgkmcnt(0)
	v_readfirstlane_b32 s2, v53
	v_subrev_co_u32_e32 v53, vcc, 1, v53
	s_ff1_i32_b32 s9, s2
	s_and_b64 s[6:7], vcc, exec
	ds_read_b32 v157, v54
	s_cselect_b32 s7, -1, s9
	s_cmp_eq_u32 s8, 0
	s_cselect_b64 s[8:9], -1, 0
	s_and_b64 s[10:11], s[8:9], exec
	s_cselect_b32 s34, s7, s28
	v_readfirstlane_b32 s6, v53
	s_cmp_lt_i32 s34, 0
	v_lshlrev_b32_e32 v210, 1, v52
	s_waitcnt lgkmcnt(0)
	s_barrier
	s_cbranch_scc1 .LBB0_655
	s_lshl_b32 s7, s34, 8
	s_add_i32 s7, s7, s29
	s_or_b32 s7, s7, s3
	v_or_b32_e32 v26, s7, v154
	v_mov_b64_e32 v[24:25], s[92:93]
	v_mad_u64_u32 v[0:1], s[10:11], v26, s97, v[24:25]
	v_lshl_add_u64 v[0:1], v[0:1], 0, s[98:99]
	v_or_b32_e32 v8, 32, v26
	v_lshl_add_u64 v[0:1], v[0:1], 0, v[210:211]
	v_mad_u64_u32 v[8:9], s[10:11], v8, s97, v[24:25]
	v_add_co_u32_e32 v4, vcc, 0x3000, v0
	v_lshl_add_u64 v[8:9], v[8:9], 0, s[98:99]
	v_or_b32_e32 v16, 64, v26
	v_addc_co_u32_e32 v5, vcc, 0, v1, vcc
	v_lshl_add_u64 v[8:9], v[8:9], 0, v[210:211]
	v_mad_u64_u32 v[16:17], s[10:11], v16, s97, v[24:25]
	v_add_co_u32_e32 v12, vcc, 0x3000, v8
	v_lshl_add_u64 v[16:17], v[16:17], 0, s[98:99]
	v_or_b32_e32 v26, 0x60, v26
	v_addc_co_u32_e32 v13, vcc, 0, v9, vcc
	v_lshl_add_u64 v[16:17], v[16:17], 0, v[210:211]
	v_mad_u64_u32 v[24:25], s[10:11], v26, s97, v[24:25]
	v_add_co_u32_e32 v20, vcc, 0x3000, v16
	v_lshl_add_u64 v[24:25], v[24:25], 0, s[98:99]
	s_nop 0
	v_addc_co_u32_e32 v21, vcc, 0, v17, vcc
	v_lshl_add_u64 v[24:25], v[24:25], 0, v[210:211]
	v_add_co_u32_e32 v28, vcc, 0x3000, v24
	global_load_dwordx4 v[0:3], v[4:5], off offset:512
	s_nop 0
	global_load_dwordx4 v[4:7], v[4:5], off offset:2560
	v_addc_co_u32_e32 v29, vcc, 0, v25, vcc
	global_load_dwordx4 v[8:11], v[12:13], off offset:512
	s_nop 0
	global_load_dwordx4 v[12:15], v[12:13], off offset:2560
	s_nop 0
	global_load_dwordx4 v[16:19], v[20:21], off offset:512
	s_nop 0
	global_load_dwordx4 v[20:23], v[20:21], off offset:2560
	s_nop 0
	global_load_dwordx4 v[24:27], v[28:29], off offset:512
	s_nop 0
	global_load_dwordx4 v[28:31], v[28:29], off offset:2560

; DEVI f32x4 mfma16(bf16x8 a, bf16x8 b, f32x4 c) { return __builtin_amdgcn_mfma_f32_16x16x32_bf16(a, b, c, 0, 0, 0); }
; template <bool OWN>
; DEVI void moba_half(const u16* Kt, const u16* Vs, const int kofs, const bf16x8 (&qb)[4], f32x4 (&oacc)[8], float& m, float& lsum,
;                     const bool lanesel, const int qinb, const int lane) {
;     ...
;   const int fr = lane & 15, fq = lane >> 4;
;   const float scl = 0.08838834764831845f * 1.4426950408889634f;
;   float s[8][4];
;   float mloc = -INFINITY;
;   const u16* kbase = Kt + (half * 128 + fr) * 136 + fq * 8;
; #pragma unroll
;   for (int kp = 0; kp < 4; ++kp) {
;     bf16x8 kf[2][4];
; #pragma unroll
;     for (int t = 0; t < 2; ++t)
; #pragma unroll
;       for (int ks = 0; ks < 4; ++ks) kf[t][ks] = *(const bf16x8*)(kbase + (2 * kp + t) * 16 * 136 + ks * 32);
;     f32x4 a0 = {0.f, 0.f, 0.f, 0.f}, a1 = {0.f, 0.f, 0.f, 0.f};
; #pragma unroll
;     for (int ks = 0; ks < 4; ++ks) { a0 = mfma16(kf[0][ks], qb[ks], a0); a1 = mfma16(kf[1][ks], qb[ks], a1); }
;     __builtin_amdgcn_sched_group_barrier(0x100, 8, 0);
;     __builtin_amdgcn_sched_group_barrier(0x008, 8, 0);
; #pragma unroll
;     for (int j = 0; j < 4; ++j) {
;       if (OWN) {
;         float v0 = ((kofs + (2 * kp) * 16 + fq * 4 + j) <= qinb) ? a0[j] * scl : -INFINITY;
;         float v1 = ((kofs + (2 * kp + 1) * 16 + fq * 4 + j) <= qinb) ? a1[j] * scl : -INFINITY;
;         s[2 * kp][j] = v0; s[2 * kp + 1][j] = v1;
;         mloc = fmaxf(mloc, fmaxf(v0, v1));
;       } else {
;         s[2 * kp][j] = a0[j]; s[2 * kp + 1][j] = a1[j];
;         mloc = fmaxf(mloc, fmaxf(a0[j], a1[j]));
;       }
;     }
;   }
; DEVI void moba_item(const Params& p, int l, int item) {
;     ...
;     const bool own = (cblk == qblk);
;     const bool lanesel = own ? true : (((mysel >> cblk) & 1u) != 0u);
;     if (own) {
;       if (chalf * 128 <= (qt & 1) * 128 + w * 16 + 15) moba_half<true>(Kc, Vc, chalf * 128, qb, oacc, m, lsum, true, qinb, lane);
;     } else if (__any(lanesel)) {
;       moba_half<false>(Kc, Vc, 0, qb, oacc, m, lsum, lanesel, qinb, lane);
.LBB0_661:
	s_and_b64 s[2:3], s[2:3], exec
	s_cselect_b32 s37, 0, s70
	s_cselect_b32 s36, s78, s72
	s_cmp_lg_u32 s38, s28
	s_mov_b64 s[2:3], -1
	s_cbranch_scc0 .LBB0_665
	v_lshrrev_b32_e32 v80, s38, v157
	v_and_b32_e32 v80, 1, v80
	v_cmp_eq_u32_e64 s[6:7], 1, v80
	v_bfe_u32 v80, v157, s38, 1
	v_cmp_ne_u32_e32 vcc, 0, v80
	s_cbranch_vccnz .Lmy_moba_body
	v_mov_b32_e32 v83, v79
	v_mov_b32_e32 v82, v78
	v_mov_b32_e32 v81, v77
	v_mov_b32_e32 v80, v76
	v_mov_b32_e32 v91, v75
	v_mov_b32_e32 v90, v74
	v_mov_b32_e32 v89, v73
	v_mov_b32_e32 v88, v72
	v_mov_b32_e32 v87, v71
	v_mov_b32_e32 v86, v70
	v_mov_b32_e32 v85, v69
	v_mov_b32_e32 v84, v68
	v_mov_b32_e32 v95, v67
	v_mov_b32_e32 v94, v66
	v_mov_b32_e32 v93, v65
	v_mov_b32_e32 v92, v64
	v_mov_b32_e32 v99, v63
	v_mov_b32_e32 v98, v62
	v_mov_b32_e32 v97, v61
	v_mov_b32_e32 v96, v60
	v_mov_b32_e32 v103, v59
	v_mov_b32_e32 v102, v58
	v_mov_b32_e32 v101, v57
	v_mov_b32_e32 v100, v56
	v_mov_b32_e32 v107, v55
	v_mov_b32_e32 v106, v54
	v_mov_b32_e32 v105, v53
	v_mov_b32_e32 v104, v52
	v_mov_b32_e32 v111, v51
	v_mov_b32_e32 v110, v50
	v_mov_b32_e32 v109, v49
	v_mov_b32_e32 v108, v48
	v_mov_b32_e32 v144, v166
	v_mov_b32_e32 v169, v167
	s_branch .LBB0_664
.Lmy_moba_body:
	v_add3_u32 v132, s37, v161, v162
	ds_read_b128 v[80:83], v132
	ds_read_b128 v[96:99], v132 offset:4352
	ds_read_b128 v[84:87], v132 offset:64
	ds_read_b128 v[100:103], v132 offset:4416
	ds_read_b128 v[88:91], v132 offset:128
	ds_read_b128 v[104:107], v132 offset:4480
	ds_read_b128 v[92:95], v132 offset:192
	ds_read_b128 v[108:111], v132 offset:4544
	v_cmp_lt_i32_e32 vcc, v232, v252
	s_waitcnt lgkmcnt(7)
	v_mfma_f32_16x16x32_bf16 v[80:83], v[80:83], v[32:35], 0
	s_waitcnt lgkmcnt(6)
	v_mfma_f32_16x16x32_bf16 v[96:99], v[96:99], v[32:35], 0
	s_waitcnt lgkmcnt(5)
	v_mfma_f32_16x16x32_bf16 v[80:83], v[84:87], v[36:39], v[80:83]
	s_waitcnt lgkmcnt(4)
	v_mfma_f32_16x16x32_bf16 v[84:87], v[100:103], v[36:39], v[96:99]
	s_waitcnt lgkmcnt(3)
	v_mfma_f32_16x16x32_bf16 v[80:83], v[88:91], v[40:43], v[80:83]
	s_waitcnt lgkmcnt(2)
	v_mfma_f32_16x16x32_bf16 v[84:87], v[104:107], v[40:43], v[84:87]
	s_waitcnt lgkmcnt(1)
	v_mfma_f32_16x16x32_bf16 v[100:103], v[92:95], v[44:47], v[80:83]
	s_waitcnt lgkmcnt(0)
	v_mfma_f32_16x16x32_bf16 v[96:99], v[108:111], v[44:47], v[84:87]
	ds_read_b128 v[104:107], v132 offset:13056
	s_nop 4
	v_max_f32_e32 v81, v100, v100
	v_max_f32_e32 v82, v101, v101
	v_max_f32_e32 v83, v103, v103
	ds_read_b128 v[84:87], v132 offset:8768
	v_max_f32_e32 v80, v96, v96
	v_max_f32_e32 v80, v81, v80
	v_max_f32_e32 v81, v97, v97
	v_max_f32_e32 v81, v82, v81
	v_max3_f32 v80, v80, s79, v81
	v_max_f32_e32 v81, v98, v98
	v_max_f32_e32 v82, v102, v102
	v_max_f32_e32 v81, v82, v81
	v_max_f32_e32 v82, v99, v99
	v_max_f32_e32 v82, v83, v82
	v_max3_f32 v120, v80, v81, v82
	ds_read_b128 v[80:83], v132 offset:8704
	ds_read_b128 v[108:111], v132 offset:13120
	ds_read_b128 v[88:91], v132 offset:8832
	ds_read_b128 v[112:115], v132 offset:13184
	ds_read_b128 v[92:95], v132 offset:8896
	ds_read_b128 v[116:119], v132 offset:13248
	s_waitcnt lgkmcnt(5)
	v_mfma_f32_16x16x32_bf16 v[80:83], v[80:83], v[32:35], 0
	v_mfma_f32_16x16x32_bf16 v[104:107], v[104:107], v[32:35], 0
	v_mfma_f32_16x16x32_bf16 v[80:83], v[84:87], v[36:39], v[80:83]
	s_waitcnt lgkmcnt(4)
	v_mfma_f32_16x16x32_bf16 v[84:87], v[108:111], v[36:39], v[104:107]
	s_waitcnt lgkmcnt(3)
	v_mfma_f32_16x16x32_bf16 v[80:83], v[88:91], v[40:43], v[80:83]
	s_waitcnt lgkmcnt(2)
	v_mfma_f32_16x16x32_bf16 v[84:87], v[112:115], v[40:43], v[84:87]
	s_waitcnt lgkmcnt(1)
	v_mfma_f32_16x16x32_bf16 v[108:111], v[92:95], v[44:47], v[80:83]
	s_waitcnt lgkmcnt(0)
	v_mfma_f32_16x16x32_bf16 v[104:107], v[116:119], v[44:47], v[84:87]
	ds_read_b128 v[112:115], v132 offset:21760
	s_nop 4
	v_max_f32_e32 v81, v108, v108
	v_max_f32_e32 v82, v109, v109
	v_max_f32_e32 v83, v111, v111
	ds_read_b128 v[84:87], v132 offset:17472
	v_max_f32_e32 v80, v104, v104
	v_max_f32_e32 v80, v81, v80
	v_max_f32_e32 v81, v105, v105
	v_max_f32_e32 v81, v82, v81
	v_max3_f32 v80, v120, v80, v81
	v_max_f32_e32 v81, v106, v106
	v_max_f32_e32 v82, v110, v110
	v_max_f32_e32 v81, v82, v81
	v_max_f32_e32 v82, v107, v107
	v_max_f32_e32 v82, v83, v82
	v_max3_f32 v128, v80, v81, v82
	ds_read_b128 v[80:83], v132 offset:17408
	ds_read_b128 v[116:119], v132 offset:21824
	ds_read_b128 v[88:91], v132 offset:17536
	ds_read_b128 v[120:123], v132 offset:21888
	ds_read_b128 v[92:95], v132 offset:17600
	ds_read_b128 v[124:127], v132 offset:21952
	s_waitcnt lgkmcnt(5)
	v_mfma_f32_16x16x32_bf16 v[80:83], v[80:83], v[32:35], 0
	v_mfma_f32_16x16x32_bf16 v[112:115], v[112:115], v[32:35], 0
	v_mfma_f32_16x16x32_bf16 v[80:83], v[84:87], v[36:39], v[80:83]
	s_waitcnt lgkmcnt(4)
	v_mfma_f32_16x16x32_bf16 v[84:87], v[116:119], v[36:39], v[112:115]
	s_waitcnt lgkmcnt(3)
	v_mfma_f32_16x16x32_bf16 v[80:83], v[88:91], v[40:43], v[80:83]
	s_waitcnt lgkmcnt(2)
	v_mfma_f32_16x16x32_bf16 v[84:87], v[120:123], v[40:43], v[84:87]
	s_waitcnt lgkmcnt(1)
	v_mfma_f32_16x16x32_bf16 v[112:115], v[92:95], v[44:47], v[80:83]
	s_waitcnt lgkmcnt(0)
	v_mfma_f32_16x16x32_bf16 v[124:127], v[124:127], v[44:47], v[84:87]
	ds_read_b128 v[116:119], v132 offset:30464
	s_nop 4
	v_max_f32_e32 v81, v112, v112
	v_max_f32_e32 v82, v113, v113
	v_max_f32_e32 v83, v115, v115
	ds_read_b128 v[84:87], v132 offset:26176
	v_max_f32_e32 v80, v124, v124
	v_max_f32_e32 v80, v81, v80
	v_max_f32_e32 v81, v125, v125
	v_max_f32_e32 v81, v82, v81
	v_max3_f32 v80, v128, v80, v81
	v_max_f32_e32 v81, v126, v126
	v_max_f32_e32 v82, v114, v114
	v_max_f32_e32 v81, v82, v81
	v_max_f32_e32 v82, v127, v127
	v_max_f32_e32 v82, v83, v82
	v_max3_f32 v136, v80, v81, v82
	ds_read_b128 v[80:83], v132 offset:26112
	ds_read_b128 v[120:123], v132 offset:30528
	ds_read_b128 v[88:91], v132 offset:26240
	ds_read_b128 v[128:131], v132 offset:30592
	ds_read_b128 v[92:95], v132 offset:26304
	ds_read_b128 v[132:135], v132 offset:30656
	s_waitcnt lgkmcnt(5)
; DEVI unsigned pk2bf(float a, float b) { hf2 v = {a, b}; hbf2 r = __builtin_convertvector(v, hbf2); return __builtin_bit_cast(unsigned, r); }
; DEVI float xq_max(float v) { v = fmaxf(v, __shfl_xor(v, 16)); v = fmaxf(v, __shfl_xor(v, 32)); return v; }
; template <bool OWN>
; DEVI void moba_half(const u16* Kt, const u16* Vs, const int kofs, const bf16x8 (&qb)[4], f32x4 (&oacc)[8], float& m, float& lsum,
;                     const bool lanesel, const int qinb, const int lane) {
;     ...
;   if (!OWN) mloc = lanesel ? mloc * scl : -INFINITY;
;   mloc = xq_max(mloc);
;   const float mnew = fmaxf(m, mloc);
;   const float alpha = __builtin_amdgcn_exp2f(m - mnew);
;   m = mnew;
;   lsum *= alpha;
; #pragma unroll
;   for (int ct = 0; ct < 8; ++ct) { oacc[ct][0] *= alpha; oacc[ct][1] *= alpha; oacc[ct][2] *= alpha; oacc[ct][3] *= alpha; }
;   const float msub = (OWN || lanesel) ? mnew : INFINITY;
;   bf16x8 pk[4];
; #pragma unroll
;   for (int pp = 0; pp < 4; ++pp) {
;     float e[8];
; #pragma unroll
;     for (int j = 0; j < 4; ++j) {
;       if (OWN) {
;         e[j] = __builtin_amdgcn_exp2f(s[2 * pp][j] - msub);
;         e[4 + j] = __builtin_amdgcn_exp2f(s[2 * pp + 1][j] - msub);
;       } else {
;         e[j] = __builtin_amdgcn_exp2f(__builtin_fmaf(s[2 * pp][j], scl, -msub));
;         e[4 + j] = __builtin_amdgcn_exp2f(__builtin_fmaf(s[2 * pp + 1][j], scl, -msub));
;       }
;     }
;     lsum += ((e[0] + e[1]) + (e[2] + e[3])) + ((e[4] + e[5]) + (e[6] + e[7]));
;     typedef __attribute__((ext_vector_type(4))) unsigned u32x4;
;     u32x4 pw = {pk2bf(e[0], e[1]), pk2bf(e[2], e[3]), pk2bf(e[4], e[5]), pk2bf(e[6], e[7])};
;     pk[pp] = __builtin_bit_cast(bf16x8, pw);
;   }
;   const int trr = (lane & 15) >> 2, trc = lane & 3;
;   const u16* vbase = Vs + (half * 128 + fq * 4 + trr) * 144 + trc * 4;
; #pragma unroll
;   for (int cp = 0; cp < 4; ++cp) {
;     bf16x4 vf[2][8];
; #pragma unroll
;     for (int t = 0; t < 2; ++t)
; #pragma unroll
;       for (int i = 0; i < 8; ++i) vf[t][i] = tr_read(vbase + i * 16 * 144 + (2 * cp + t) * 16);
	v_mfma_f32_16x16x32_bf16 v[80:83], v[80:83], v[32:35], 0
	v_mfma_f32_16x16x32_bf16 v[116:119], v[116:119], v[32:35], 0
	v_mfma_f32_16x16x32_bf16 v[80:83], v[84:87], v[36:39], v[80:83]
	s_waitcnt lgkmcnt(4)
	v_mfma_f32_16x16x32_bf16 v[84:87], v[120:123], v[36:39], v[116:119]
	s_waitcnt lgkmcnt(3)
	v_mfma_f32_16x16x32_bf16 v[80:83], v[88:91], v[40:43], v[80:83]
	s_waitcnt lgkmcnt(2)
	v_mfma_f32_16x16x32_bf16 v[84:87], v[128:131], v[40:43], v[84:87]
	s_waitcnt lgkmcnt(1)
	v_mfma_f32_16x16x32_bf16 v[144:147], v[92:95], v[44:47], v[80:83]
	s_waitcnt lgkmcnt(0)
	v_mfma_f32_16x16x32_bf16 v[148:151], v[132:135], v[44:47], v[84:87]
	s_nop 5
	v_max_f32_e32 v81, v144, v144
	s_nop 0
	v_max_f32_e32 v80, v148, v148
	v_max_f32_e32 v80, v81, v80
	v_max_f32_e32 v81, v149, v149
	v_max_f32_e32 v82, v145, v145
	v_max_f32_e32 v81, v82, v81
	v_max3_f32 v80, v136, v80, v81
	v_max_f32_e32 v81, v150, v150
	v_max_f32_e32 v82, v146, v146
	v_max_f32_e32 v81, v82, v81
	v_max_f32_e32 v82, v151, v151
	v_max_f32_e32 v83, v147, v147
	v_max_f32_e32 v82, v83, v82
	v_max3_f32 v80, v80, v81, v82
	v_mul_f32_e32 v80, 0x3e0293ee, v80
	v_cndmask_b32_e32 v81, v235, v232, vcc
	v_cndmask_b32_e64 v80, v233, v80, s[6:7]
	v_lshlrev_b32_e32 v81, 2, v81
	ds_bpermute_b32 v81, v81, v80
	v_cmp_lt_i32_e32 vcc, v226, v252
	s_waitcnt lgkmcnt(0)
	v_max_f32_e32 v81, v81, v81
	v_max_f32_e32 v80, v80, v81
	v_cndmask_b32_e32 v81, v235, v226, vcc
	v_lshlrev_b32_e32 v81, 2, v81
	ds_bpermute_b32 v81, v81, v80
	s_waitcnt lgkmcnt(0)
	v_max3_f32 v169, v167, v80, v81
	v_cndmask_b32_e64 v170, v233, -v169, s[6:7]
	v_fmamk_f32 v96, v96, 0x3e0293ee, v170
	v_fmamk_f32 v100, v100, 0x3e0293ee, v170
	v_exp_f32_e32 v117, v96
	v_fmamk_f32 v96, v101, 0x3e0293ee, v170
	v_fmamk_f32 v97, v97, 0x3e0293ee, v170
	v_fmamk_f32 v98, v98, 0x3e0293ee, v170
	v_exp_f32_e32 v116, v100
	v_exp_f32_e32 v96, v96
	v_exp_f32_e32 v97, v97
	v_fmamk_f32 v100, v102, 0x3e0293ee, v170
	v_exp_f32_e32 v101, v98
	v_fmamk_f32 v98, v103, 0x3e0293ee, v170
	v_fmamk_f32 v99, v99, 0x3e0293ee, v170
	v_exp_f32_e32 v100, v100
	v_exp_f32_e32 v98, v98
	v_exp_f32_e32 v99, v99
	v_pk_add_f32 v[102:103], v[116:117], v[96:97]
	v_cvt_pk_bf16_f32 v122, v117, v97
	v_fmamk_f32 v97, v104, 0x3e0293ee, v170
	v_pk_add_f32 v[118:119], v[100:101], v[98:99]
	v_cvt_pk_bf16_f32 v121, v100, v98
	v_exp_f32_e32 v98, v97
	v_fmamk_f32 v97, v109, 0x3e0293ee, v170
	v_pk_add_f32 v[102:103], v[102:103], v[118:119]
	v_exp_f32_e32 v100, v97
	v_fmamk_f32 v97, v105, 0x3e0293ee, v170
	v_pk_add_f32 v[102:103], v[102:103], v[102:103] op_sel_hi:[0,1]
	v_cvt_pk_bf16_f32 v120, v116, v96
	v_cvt_pk_bf16_f32 v123, v101, v99
	v_fmamk_f32 v96, v108, 0x3e0293ee, v170
	v_exp_f32_e32 v104, v97
	v_fmamk_f32 v97, v110, 0x3e0293ee, v170
	v_fmamk_f32 v101, v111, 0x3e0293ee, v170
	v_exp_f32_e32 v96, v96
	v_exp_f32_e32 v97, v97
	v_fmamk_f32 v99, v106, 0x3e0293ee, v170
	v_exp_f32_e32 v101, v101
	v_fmamk_f32 v102, v107, 0x3e0293ee, v170
	v_exp_f32_e32 v99, v99
	v_exp_f32_e32 v105, v102
	v_pk_add_f32 v[106:107], v[96:97], v[100:101]
	v_cvt_pk_bf16_f32 v117, v97, v101
	v_fmamk_f32 v97, v124, 0x3e0293ee, v170
	v_pk_add_f32 v[108:109], v[98:99], v[104:105]
	v_cvt_pk_bf16_f32 v118, v98, v104
	v_exp_f32_e32 v98, v97
	v_fmamk_f32 v97, v113, 0x3e0293ee, v170
	v_cvt_pk_bf16_f32 v116, v96, v100
	v_exp_f32_e32 v100, v97
	v_fmamk_f32 v97, v125, 0x3e0293ee, v170
	v_exp_f32_e32 v102, v97
	v_fmamk_f32 v97, v114, 0x3e0293ee, v170
	v_pk_add_f32 v[106:107], v[106:107], v[106:107] op_sel_hi:[0,1]
	v_exp_f32_e32 v104, v97
	v_fmamk_f32 v97, v126, 0x3e0293ee, v170
	v_pk_add_f32 v[108:109], v[108:109], v[108:109] op_sel_hi:[0,1]
	v_fmamk_f32 v96, v112, 0x3e0293ee, v170
	v_exp_f32_e32 v106, v97
	v_fmamk_f32 v97, v115, 0x3e0293ee, v170
	v_exp_f32_e32 v96, v96
	v_exp_f32_e32 v108, v97
	v_fmamk_f32 v97, v127, 0x3e0293ee, v170
	v_exp_f32_e32 v110, v97
	v_add_f32_e32 v97, v96, v100
	v_add_f32_e32 v101, v98, v102
	v_cvt_pk_bf16_f32 v124, v96, v100
	v_cvt_pk_bf16_f32 v126, v98, v102
	v_fmamk_f32 v98, v148, 0x3e0293ee, v170
	v_fmamk_f32 v100, v149, 0x3e0293ee, v170
	v_fmamk_f32 v102, v150, 0x3e0293ee, v170
	v_sub_f32_e32 v80, v167, v169
	v_cvt_pk_bf16_f32 v119, v99, v105
	v_add_f32_e32 v99, v104, v108
	v_add_f32_e32 v105, v106, v110
	v_cvt_pk_bf16_f32 v125, v104, v108
	v_cvt_pk_bf16_f32 v127, v106, v110
	v_fmamk_f32 v96, v144, 0x3e0293ee, v170
	v_exp_f32_e32 v106, v98
	v_fmamk_f32 v98, v145, 0x3e0293ee, v170
	v_exp_f32_e32 v108, v100
	v_fmamk_f32 v100, v146, 0x3e0293ee, v170
	v_exp_f32_e32 v152, v102
	v_fmamk_f32 v102, v147, 0x3e0293ee, v170
	v_exp_f32_e32 v82, v80
	v_exp_f32_e32 v96, v96
	v_exp_f32_e32 v98, v98
	v_exp_f32_e32 v100, v100
	v_exp_f32_e32 v104, v102
	v_fmac_f32_e32 v170, 0x3e0293ee, v151
	v_exp_f32_e32 v102, v170
	v_mul_f32_e32 v153, v166, v82
	v_pk_add_f32 v[110:111], v[96:97], v[98:99]
	v_pk_add_f32 v[112:113], v[100:101], v[104:105]
	v_pk_add_f32 v[114:115], v[152:153], v[102:103]
	v_pk_add_f32 v[110:111], v[110:111], v[112:113]
	v_pk_add_f32 v[112:113], v[106:107], v[108:109]
	v_pk_mul_f32 v[140:141], v[48:49], v[82:83] op_sel_hi:[1,0]
	v_pk_add_f32 v[112:113], v[112:113], v[114:115]
	v_cvt_pk_bf16_f32 v115, v152, v102
	v_pk_add_f32 v[110:111], v[110:111], v[112:113]
	v_cvt_pk_bf16_f32 v112, v96, v98
	v_lshlrev_b32_e32 v96, 1, v164
	v_add3_u32 v145, s36, v163, v96
	ds_read_b64_tr_b16 v[98:99], v145 offset:4608
	ds_read_b64_tr_b16 v[96:97], v145
	ds_read_b64_tr_b16 v[146:147], v145 offset:32
	ds_read_b64_tr_b16 v[148:149], v145 offset:4640
	v_cvt_pk_bf16_f32 v113, v100, v104
	ds_read_b64_tr_b16 v[100:101], v145 offset:9216
	ds_read_b64_tr_b16 v[102:103], v145 offset:13824
	ds_read_b64_tr_b16 v[150:151], v145 offset:9248
	ds_read_b64_tr_b16 v[152:153], v145 offset:13856
	v_pk_mul_f32 v[142:143], v[50:51], v[82:83] op_sel_hi:[1,0]
	v_pk_mul_f32 v[136:137], v[52:53], v[82:83] op_sel_hi:[1,0]
	v_pk_mul_f32 v[138:139], v[54:55], v[82:83] op_sel_hi:[1,0]
	v_cvt_pk_bf16_f32 v114, v106, v108
	ds_read_b64_tr_b16 v[104:105], v145 offset:18432
	ds_read_b64_tr_b16 v[106:107], v145 offset:23040
	ds_read_b64_tr_b16 v[170:171], v145 offset:18464
	ds_read_b64_tr_b16 v[172:173], v145 offset:23072
	v_add_f32_e32 v144, v110, v111
	ds_read_b64_tr_b16 v[108:109], v145 offset:27648
	ds_read_b64_tr_b16 v[110:111], v145 offset:32256
	ds_read_b64_tr_b16 v[174:175], v145 offset:27680
	ds_read_b64_tr_b16 v[176:177], v145 offset:32288
	s_waitcnt lgkmcnt(14)
; DEVI bf16x8 cat8(bf16x4 a, bf16x4 b) { return __builtin_shufflevector(a, b, 0, 1, 2, 3, 4, 5, 6, 7); }
; DEVI f32x4 mfma16(bf16x8 a, bf16x8 b, f32x4 c) { return __builtin_amdgcn_mfma_f32_16x16x32_bf16(a, b, c, 0, 0, 0); }
; template <bool OWN>
; DEVI void moba_half(const u16* Kt, const u16* Vs, const int kofs, const bf16x8 (&qb)[4], f32x4 (&oacc)[8], float& m, float& lsum,
;                     const bool lanesel, const int qinb, const int lane) {
;     ...
;   const int trr = (lane & 15) >> 2, trc = lane & 3;
;   const u16* vbase = Vs + (half * 128 + fq * 4 + trr) * 144 + trc * 4;
; #pragma unroll
;   for (int cp = 0; cp < 4; ++cp) {
;     bf16x4 vf[2][8];
; #pragma unroll
;     for (int t = 0; t < 2; ++t)
; #pragma unroll
;       for (int i = 0; i < 8; ++i) vf[t][i] = tr_read(vbase + i * 16 * 144 + (2 * cp + t) * 16);
; #pragma unroll
;     for (int pp = 0; pp < 4; ++pp) {
;       oacc[2 * cp] = mfma16(cat8(vf[0][2 * pp], vf[0][2 * pp + 1]), pk[pp], oacc[2 * cp]);
;       oacc[2 * cp + 1] = mfma16(cat8(vf[1][2 * pp], vf[1][2 * pp + 1]), pk[pp], oacc[2 * cp + 1]);
;     }
;     __builtin_amdgcn_sched_group_barrier(0x100, 16, 0);
;     __builtin_amdgcn_sched_group_barrier(0x008, 8, 0);
;   }
	v_mfma_f32_16x16x32_bf16 v[96:99], v[96:99], v[120:123], v[140:143]
	v_mul_f32_e64 v132, v56, v82
	v_mul_f32_e64 v133, v57, v82
	v_pk_mul_f32 v[134:135], v[58:59], v[82:83] op_sel_hi:[1,0]
	v_pk_mul_f32 v[128:129], v[60:61], v[82:83] op_sel_hi:[1,0]
	s_waitcnt lgkmcnt(12)
	v_mfma_f32_16x16x32_bf16 v[136:139], v[146:149], v[120:123], v[136:139]
	v_mul_f32_e64 v130, v62, v82
	v_mul_f32_e64 v131, v63, v82
	v_pk_mul_f32 v[92:93], v[64:65], v[82:83] op_sel_hi:[1,0]
	v_pk_mul_f32 v[94:95], v[66:67], v[82:83] op_sel_hi:[1,0]
	s_waitcnt lgkmcnt(10)
	v_mfma_f32_16x16x32_bf16 v[96:99], v[100:103], v[116:119], v[96:99]
	v_mul_f32_e64 v84, v68, v82
	v_mul_f32_e64 v85, v69, v82
	v_pk_mul_f32 v[86:87], v[70:71], v[82:83] op_sel_hi:[1,0]
	v_pk_mul_f32 v[88:89], v[72:73], v[82:83] op_sel_hi:[1,0]
	s_waitcnt lgkmcnt(8)
	v_mfma_f32_16x16x32_bf16 v[100:103], v[150:153], v[116:119], v[136:139]
	v_mul_f32_e64 v90, v74, v82
	v_mul_f32_e64 v91, v75, v82
	v_pk_mul_f32 v[80:81], v[76:77], v[82:83] op_sel_hi:[1,0]
	v_pk_mul_f32 v[82:83], v[78:79], v[82:83] op_sel_hi:[1,0]
	s_waitcnt lgkmcnt(6)
	v_mfma_f32_16x16x32_bf16 v[96:99], v[104:107], v[124:127], v[96:99]
	s_waitcnt lgkmcnt(4)
	v_mfma_f32_16x16x32_bf16 v[100:103], v[170:173], v[124:127], v[100:103]
	s_waitcnt lgkmcnt(2)
	v_mfma_f32_16x16x32_bf16 v[108:111], v[108:111], v[112:115], v[96:99]
	s_waitcnt lgkmcnt(0)
	v_mfma_f32_16x16x32_bf16 v[104:107], v[174:177], v[112:115], v[100:103]
	s_nop 1
	ds_read_b64_tr_b16 v[98:99], v145 offset:4672
	ds_read_b64_tr_b16 v[96:97], v145 offset:64
	ds_read_b64_tr_b16 v[146:147], v145 offset:96
	ds_read_b64_tr_b16 v[148:149], v145 offset:4704
	ds_read_b64_tr_b16 v[100:101], v145 offset:9280
	ds_read_b64_tr_b16 v[102:103], v145 offset:13888
	ds_read_b64_tr_b16 v[150:151], v145 offset:9312
	ds_read_b64_tr_b16 v[152:153], v145 offset:13920
	ds_read_b64_tr_b16 v[136:137], v145 offset:18496
	ds_read_b64_tr_b16 v[138:139], v145 offset:23104
	ds_read_b64_tr_b16 v[170:171], v145 offset:18528
	ds_read_b64_tr_b16 v[172:173], v145 offset:23136
	ds_read_b64_tr_b16 v[140:141], v145 offset:27712
	ds_read_b64_tr_b16 v[142:143], v145 offset:32320
	ds_read_b64_tr_b16 v[174:175], v145 offset:27744
	ds_read_b64_tr_b16 v[176:177], v145 offset:32352
	s_waitcnt lgkmcnt(14)
	v_mfma_f32_16x16x32_bf16 v[96:99], v[96:99], v[120:123], v[132:135]
	s_waitcnt lgkmcnt(12)
	v_mfma_f32_16x16x32_bf16 v[128:131], v[146:149], v[120:123], v[128:131]
	s_waitcnt lgkmcnt(10)
	v_mfma_f32_16x16x32_bf16 v[96:99], v[100:103], v[116:119], v[96:99]
	s_waitcnt lgkmcnt(8)
	v_mfma_f32_16x16x32_bf16 v[100:103], v[150:153], v[116:119], v[128:131]
	s_waitcnt lgkmcnt(6)
	v_mfma_f32_16x16x32_bf16 v[96:99], v[136:139], v[124:127], v[96:99]
	s_waitcnt lgkmcnt(4)
	v_mfma_f32_16x16x32_bf16 v[128:131], v[170:173], v[124:127], v[100:103]
	s_waitcnt lgkmcnt(2)
	v_mfma_f32_16x16x32_bf16 v[100:103], v[140:143], v[112:115], v[96:99]
	s_waitcnt lgkmcnt(0)
	v_mfma_f32_16x16x32_bf16 v[96:99], v[174:177], v[112:115], v[128:131]
	ds_read_b64_tr_b16 v[146:147], v145 offset:160
	ds_read_b64_tr_b16 v[148:149], v145 offset:4768
	ds_read_b64_tr_b16 v[132:133], v145 offset:9344
	s_nop 0
	ds_read_b64_tr_b16 v[130:131], v145 offset:4736
	ds_read_b64_tr_b16 v[128:129], v145 offset:128
	ds_read_b64_tr_b16 v[134:135], v145 offset:13952
	ds_read_b64_tr_b16 v[150:151], v145 offset:9376
	ds_read_b64_tr_b16 v[152:153], v145 offset:13984
	ds_read_b64_tr_b16 v[136:137], v145 offset:18560
	ds_read_b64_tr_b16 v[138:139], v145 offset:23168
	ds_read_b64_tr_b16 v[170:171], v145 offset:18592
	ds_read_b64_tr_b16 v[172:173], v145 offset:23200
	ds_read_b64_tr_b16 v[140:141], v145 offset:27776
	ds_read_b64_tr_b16 v[142:143], v145 offset:32384
	ds_read_b64_tr_b16 v[174:175], v145 offset:27808
	ds_read_b64_tr_b16 v[176:177], v145 offset:32416
	s_waitcnt lgkmcnt(11)
	v_mfma_f32_16x16x32_bf16 v[92:95], v[128:131], v[120:123], v[92:95]
	v_mfma_f32_16x16x32_bf16 v[84:87], v[146:149], v[120:123], v[84:87]
	s_waitcnt lgkmcnt(10)
	v_mfma_f32_16x16x32_bf16 v[92:95], v[132:135], v[116:119], v[92:95]
	s_waitcnt lgkmcnt(8)
	v_mfma_f32_16x16x32_bf16 v[84:87], v[150:153], v[116:119], v[84:87]
	s_waitcnt lgkmcnt(6)
	v_mfma_f32_16x16x32_bf16 v[92:95], v[136:139], v[124:127], v[92:95]
	s_waitcnt lgkmcnt(4)
	v_mfma_f32_16x16x32_bf16 v[84:87], v[170:173], v[124:127], v[84:87]
	s_waitcnt lgkmcnt(2)
	v_mfma_f32_16x16x32_bf16 v[92:95], v[140:143], v[112:115], v[92:95]
	s_waitcnt lgkmcnt(0)
	v_mfma_f32_16x16x32_bf16 v[84:87], v[174:177], v[112:115], v[84:87]
	ds_read_b64_tr_b16 v[130:131], v145 offset:4800
	ds_read_b64_tr_b16 v[128:129], v145 offset:192
	ds_read_b64_tr_b16 v[146:147], v145 offset:224
	ds_read_b64_tr_b16 v[148:149], v145 offset:4832
	ds_read_b64_tr_b16 v[132:133], v145 offset:9408
	ds_read_b64_tr_b16 v[134:135], v145 offset:14016
	ds_read_b64_tr_b16 v[150:151], v145 offset:9440
	ds_read_b64_tr_b16 v[152:153], v145 offset:14048
	ds_read_b64_tr_b16 v[136:137], v145 offset:18624
	ds_read_b64_tr_b16 v[138:139], v145 offset:23232
	ds_read_b64_tr_b16 v[170:171], v145 offset:18656
	ds_read_b64_tr_b16 v[172:173], v145 offset:23264
	ds_read_b64_tr_b16 v[140:141], v145 offset:27840
	ds_read_b64_tr_b16 v[142:143], v145 offset:32448
	ds_read_b64_tr_b16 v[174:175], v145 offset:27872
	ds_read_b64_tr_b16 v[176:177], v145 offset:32480
	s_waitcnt lgkmcnt(14)
	v_mfma_f32_16x16x32_bf16 v[88:91], v[128:131], v[120:123], v[88:91]
	s_waitcnt lgkmcnt(12)
	v_mfma_f32_16x16x32_bf16 v[80:83], v[146:149], v[120:123], v[80:83]
	s_waitcnt lgkmcnt(10)
	v_mfma_f32_16x16x32_bf16 v[88:91], v[132:135], v[116:119], v[88:91]
	s_waitcnt lgkmcnt(8)
	v_mfma_f32_16x16x32_bf16 v[80:83], v[150:153], v[116:119], v[80:83]
	s_waitcnt lgkmcnt(6)
	v_mfma_f32_16x16x32_bf16 v[88:91], v[136:139], v[124:127], v[88:91]
	s_waitcnt lgkmcnt(4)
	v_mfma_f32_16x16x32_bf16 v[80:83], v[170:173], v[124:127], v[80:83]
	s_waitcnt lgkmcnt(2)
	v_mfma_f32_16x16x32_bf16 v[88:91], v[140:143], v[112:115], v[88:91]
	s_waitcnt lgkmcnt(0)
	v_mfma_f32_16x16x32_bf16 v[80:83], v[174:177], v[112:115], v[80:83]
